# GEMM K-loop: per-block s_setprio flips deleted, one static s_setprio 1 for waves 4-7 (reset at phase end)
# speedup vs baseline: 1.0033x; 1.0033x over previous
; DI int opq_tid() { int t = threadIdx.x; asm volatile("" : "+v"(t)); return t; }
; #define PG8_STAGE(bufoff, gbase, voff) do { _Pragma("unroll") for (int _i = 0; _i < 2; ++_i) \
;         __builtin_amdgcn_global_load_lds((const unsigned*)((const char*)(gbase) + (voff)[_i]), (LAS unsigned*)(lds + (bufoff) + ldsw + _i * 8192), 16, 0, 0); } while (0)
; #define PG8_BAR __builtin_amdgcn_s_barrier()
; DI void gemm_phase(LAS unsigned char* lds, const Sched& S, const Epi& Ep) {
;     const int tid = opq_tid(), wid = __builtin_amdgcn_readfirstlane(tid >> 6), lane = tid & 63, wr = wid >> 2, wc = wid & 3, fr = lane & 15, fq = lane >> 4;
;     const int K = S.K, nt = K / BK;
;     unsigned voffA[2], voffB[2];
; #pragma unroll
;     for (int i = 0; i < 2; ++i) { int R, C; stage_rc(tid * 16 + i * 8192, R, C); const int Rb = Ep.PERM ? ((R & ~31) + perm32(R & 31)) : R;
;         voffA[i] = (unsigned)(R * S.lda + C) * 2u; voffB[i] = (unsigned)(Rb * S.ldb + C) * 2u; }
;     const size_t kstep = (size_t)(BK * 2);
;     const size_t hstepA = (size_t)HALF * S.lda * 2, hstepB = (size_t)HALF * S.ldb * 2;
;     const unsigned ldsw = (unsigned)wid * 1024u;
;     const int aoff = lds_byte(wr * 64 + fr, fq * 8), boff = lds_byte(wc * 32 + fr, fq * 8);
;     ...
;     Unit cur, nxt; int ui = 0;
;     if (!S.next(0, cur)) return;
;     f32x4 acc[2][2][4][2];
; #pragma unroll
;     for (int a = 0; a < 2; ++a)
; #pragma unroll
;         for (int b = 0; b < 2; ++b)
; #pragma unroll
;             for (int m = 0; m < 4; ++m)
; #pragma unroll
;                 for (int n = 0; n < 2; ++n) acc[a][b][m][n] = (f32x4){0.f, 0.f, 0.f, 0.f};
;     bf16x8 At[4][2], B0[2][2], B1[2][2];
;     const char* cA = S.pa(cur); const char* cB = S.pb(cur);
;     PG8_STAGE(PG8_SB(0, 0), cB, voffB); PG8_STAGE(PG8_SB(0, 1), cB + hstepB, voffB); PG8_STAGE(PG8_SA(0, 0), cA, voffA); PG8_STAGE(PG8_SA(0, 1), cA + hstepA, voffA);
;     if (wr == 1) PG8_BAR;
.LBB0_331:
	v_bfe_i32 v4, v0, 27, 1
	v_lshlrev_b32_e32 v2, 4, v0
	v_lshrrev_b32_e32 v4, 22, v4
	v_add_u32_e32 v4, v2, v4
	v_and_b32_e32 v4, 0xfffffc00, v4
	v_ashrrev_i32_e32 v3, 31, v0
	v_sub_u32_e32 v4, v2, v4
	v_lshrrev_b32_e32 v3, 26, v3
	v_lshrrev_b32_e32 v5, 4, v4
	v_add_u32_e32 v3, v0, v3
	v_bitop3_b32 v5, v5, v4, 32 bitop3:0x6c
	v_ashrrev_i32_e32 v4, 31, v4
	v_ashrrev_i32_e32 v3, 6, v3
	v_lshrrev_b32_e32 v4, 26, v4
	v_lshlrev_b32_e32 v6, 3, v3
	v_add_u32_e32 v4, v5, v4
	v_and_b32_e32 v6, -16, v6
	v_ashrrev_i32_e32 v4, 6, v4
	v_lshlrev_b32_e32 v3, 5, v3
	v_add_u32_e32 v6, v4, v6
	v_and_b32_e32 v14, 32, v3
	v_mul_i32_i24_e32 v3, 64, v4
	v_sub_u32_e32 v3, v5, v3
	v_mov_b32_e32 v8, 1
	v_lshlrev_b32_e32 v5, 1, v6
	v_lshrrev_b32_e32 v7, 2, v6
	v_and_b32_e32 v4, 3, v4
	s_movk_i32 s10, 0xffe0
	v_ashrrev_i16_sdwa v3, v8, sext(v3) dst_sel:DWORD dst_unused:UNUSED_PAD src0_sel:DWORD src1_sel:BYTE_0
	v_and_b32_e32 v5, 24, v5
	v_and_b32_e32 v7, 4, v7
	v_and_or_b32 v4, v6, s10, v4
	v_bfe_i32 v15, v3, 0, 16
	v_or3_b32 v4, v4, v7, v5
	v_add_u32_e32 v3, v14, v15
	v_mul_lo_u32 v16, v6, s53
	v_mul_lo_u32 v4, v4, s52
	v_add_u32_e32 v2, 0x2000, v2
	v_add_lshl_u32 v194, v3, v16, 1
	v_add_lshl_u32 v196, v4, v3, 1
	v_ashrrev_i32_e32 v3, 31, v2
	v_lshrrev_b32_e32 v3, 22, v3
	v_add_u32_e32 v3, v2, v3
	v_ashrrev_i32_e32 v3, 10, v3
	v_mul_i32_i24_e32 v4, 0x400, v3
	v_sub_u32_e32 v2, v2, v4
	v_lshrrev_b32_e32 v4, 4, v2
	v_bitop3_b32 v2, v4, v2, 32 bitop3:0x6c
	v_ashrrev_i32_e32 v5, 31, v2
	v_lshrrev_b32_e32 v5, 26, v5
	v_lshlrev_b32_e32 v4, 3, v3
	v_add_u32_e32 v5, v2, v5
	v_and_b32_e32 v4, -16, v4
	v_ashrrev_i32_e32 v6, 6, v5
	v_lshlrev_b32_e32 v3, 5, v3
	s_ashr_i32 s3, s8, 6
	v_add_u32_e32 v4, v6, v4
	v_and_b32_e32 v17, 32, v3
	v_and_b32_e32 v3, 0xc0, v5
	v_sub_u32_e32 v2, v2, v3
	v_lshlrev_b32_e32 v3, 1, v4
	v_lshrrev_b32_e32 v5, 2, v4
	v_and_b32_e32 v6, 3, v6
	s_lshl_b32 s19, s3, 10
	v_ashrrev_i16_sdwa v2, v8, sext(v2) dst_sel:DWORD dst_unused:UNUSED_PAD src0_sel:DWORD src1_sel:BYTE_0
	v_and_b32_e32 v3, 24, v3
	v_and_b32_e32 v5, 4, v5
	v_and_or_b32 v6, v4, s10, v6
	s_add_i32 s96, s19, 0
	v_bfe_i32 v18, v2, 0, 16
	v_or3_b32 v3, v6, v5, v3
	s_add_i32 m0, s96, 0x10000
	v_add_u32_e32 v2, v17, v18
	v_mul_lo_u32 v3, v3, s52
	s_ashr_i32 s15, s8, 8
	global_load_lds_dwordx4 v196, s[44:45]
	s_add_i32 m0, s96, 0x12000
	v_add_lshl_u32 v200, v3, v2, 1
	s_add_u32 s12, s44, s77
	global_load_lds_dwordx4 v200, s[44:45]
	s_addc_u32 s13, s45, 0
	s_add_i32 m0, s96, 0x14000
	v_mov_b32_e32 v197, v1
	v_mov_b32_e32 v201, v1
	global_load_lds_dwordx4 v196, s[12:13]
	s_add_i32 m0, s96, 0x16000
	s_add_i32 s90, s96, 0x2000
	v_mul_lo_u32 v19, v4, s53
	v_lshl_add_u64 v[6:7], s[12:13], 0, v[196:197]
	v_lshl_add_u64 v[8:9], s[12:13], 0, v[200:201]
	global_load_lds_dwordx4 v200, s[12:13]
	s_mov_b32 m0, s96
	s_add_u32 s12, s46, s6
	v_add_lshl_u32 v198, v2, v19, 1
	global_load_lds_dwordx4 v194, s[46:47]
	s_mov_b32 m0, s90
	s_addc_u32 s13, s47, 0
	s_add_i32 s91, s96, 0x4000
	global_load_lds_dwordx4 v198, s[46:47]
	s_mov_b32 m0, s91
	s_add_i32 s28, s96, 0x6000
	global_load_lds_dwordx4 v194, s[12:13]
	s_mov_b32 m0, s28
	v_writelane_b32 v255, s62, 26
	global_load_lds_dwordx4 v198, s[12:13]
	s_nop 0
	v_writelane_b32 v255, s63, 27
	v_writelane_b32 v255, s60, 28
	v_mov_b32_e32 v195, v1
	v_mov_b32_e32 v199, v1
	v_writelane_b32 v255, s61, 29
	v_writelane_b32 v255, s30, 30
	s_cmp_eq_u32 s15, 1
	v_lshl_add_u64 v[2:3], s[44:45], 0, v[196:197]
	v_writelane_b32 v255, s31, 31
	v_writelane_b32 v255, s58, 32
	v_lshl_add_u64 v[4:5], s[44:45], 0, v[200:201]
	v_lshl_add_u64 v[10:11], s[46:47], 0, v[194:195]
	v_writelane_b32 v255, s59, 33
	v_writelane_b32 v255, s56, 34
	v_lshl_add_u64 v[12:13], s[46:47], 0, v[198:199]
	s_cselect_b64 s[16:17], -1, 0
	v_writelane_b32 v255, s57, 35
	s_cmp_lg_u32 s15, 1
	s_cbranch_scc1 .LBB0_333
	s_barrier
	s_setprio 1

; #define PG8_STAGE(bufoff, gbase, voff) do { _Pragma("unroll") for (int _i = 0; _i < 2; ++_i) \
;         __builtin_amdgcn_global_load_lds((const unsigned*)((const char*)(gbase) + (voff)[_i]), (LAS unsigned*)(lds + (bufoff) + ldsw + _i * 8192), 16, 0, 0); } while (0)
; #define PG8_LDA(dst, b, h) do { _Pragma("unroll") for (int m = 0; m < 4; ++m) _Pragma("unroll") for (int k = 0; k < 2; ++k) dst[m][k] = *(const LAS bf16x8*)(lds + PG8_SA(b, h) + aoff + m * 2048 + k * 1024); } while (0)
; #define PG8_LDB(dst, b, h) do { _Pragma("unroll") for (int n = 0; n < 2; ++n) _Pragma("unroll") for (int k = 0; k < 2; ++k) dst[n][k] = *(const LAS bf16x8*)(lds + PG8_SB(b, h) + boff + n * 2048 + k * 1024); } while (0)
; #define PG8_MMA(ai, bj, At, Bt) do { __builtin_amdgcn_s_setprio(1); _Pragma("unroll") for (int m = 0; m < 4; ++m) _Pragma("unroll") for (int n = 0; n < 2; ++n) _Pragma("unroll") for (int k = 0; k < 2; ++k) \
;         acc[ai][bj][m][n] = __builtin_amdgcn_mfma_f32_16x16x32_bf16(Bt[n][k], At[m][k], acc[ai][bj][m][n], 0, 0, 0); __builtin_amdgcn_s_setprio(0); } while (0)
; #define PG8_WAIT_V(n) asm volatile("s_waitcnt vmcnt(" #n ")" ::: "memory")
; #define PG8_WAIT_L(n) asm volatile("s_waitcnt lgkmcnt(" #n ")" ::: "memory")
; #define PG8_BAR __builtin_amdgcn_s_barrier()
; #define PG8_SCHED __builtin_amdgcn_sched_barrier(0)
; DI void gemm_phase(LAS unsigned char* lds, const Sched& S, const Epi& Ep) {
;     ...
;             const char* a1 = cA + (size_t)(t + 1) * kstep;
;             const char* a2 = last ? nA : cA + (size_t)(t + 2) * kstep; const char* b2 = last ? nB : cB + (size_t)(t + 2) * kstep;
;             const char* a3 = a2 + kstep; const char* b3 = b2 + kstep;
;             PG8_LDB(B0, 0, 0); PG8_LDB(B1, 0, 1); PG8_SCHED; PG8_LDA(At, 0, 0); PG8_STAGE(PG8_SA(1, 1), a1 + hstepA, voffA);
;             PG8_WAIT_V(8); PG8_WAIT_L(0); PG8_BAR; PG8_MMA(0, 0, At, B0); PG8_MMA(0, 1, At, B1); PG8_BAR; PG8_SCHED;
;             PG8_LDA(At, 0, 1); PG8_STAGE(PG8_SB(0, 0), b2, voffB); PG8_STAGE(PG8_SB(0, 1), b2 + hstepB, voffB); PG8_STAGE(PG8_SA(0, 0), a2, voffA);
.LBB0_370:
	s_add_i32 s3, s3, 2
	s_add_u32 s8, s46, s44
	s_addc_u32 s12, s47, s45
	s_add_u32 s8, s8, 0x100
	s_addc_u32 s12, s12, 0
	s_add_u32 s24, s64, s44
	s_addc_u32 s13, s10, s45
	s_add_i32 s25, 0, 0x10000
	s_cmp_eq_u32 s7, s44
	s_cselect_b32 s17, s1, s12
	s_cselect_b32 s16, s0, s8
	v_add_u32_e32 v0, s25, v252
	s_cselect_b32 s13, s79, s13
	s_cselect_b32 s12, s78, s24
	s_add_i32 s8, 0, 0x14000
	ds_read_b128 v[134:137], v0
	ds_read_b128 v[138:141], v0 offset:1024
	ds_read_b128 v[142:145], v0 offset:2048
	ds_read_b128 v[146:149], v0 offset:3072
	v_add_u32_e32 v0, s8, v252
	ds_read_b128 v[150:153], v0
	ds_read_b128 v[154:157], v0 offset:1024
	ds_read_b128 v[158:161], v0 offset:2048
	ds_read_b128 v[162:165], v0 offset:3072
	v_lshl_add_u64 v[210:211], v[132:133], 0, s[44:45]
	s_add_i32 m0, s96, 0xc000
	ds_read_b128 v[166:169], v249
	ds_read_b128 v[170:173], v249 offset:1024
	ds_read_b128 v[174:177], v249 offset:2048
	ds_read_b128 v[178:181], v249 offset:3072
	ds_read_b128 v[182:185], v249 offset:4096
	ds_read_b128 v[186:189], v249 offset:5120
	ds_read_b128 v[190:193], v249 offset:6144
	ds_read_b128 v[206:209], v249 offset:7168
	global_load_lds_dwordx4 v[210:211], off
	v_lshl_add_u64 v[210:211], v[130:131], 0, s[44:45]
	s_add_i32 m0, s96, 0xe000
	s_nop 0
	global_load_lds_dwordx4 v[210:211], off
	s_waitcnt vmcnt(8)
	s_waitcnt lgkmcnt(0)
	s_barrier
	s_waitcnt lgkmcnt(0)
	v_mfma_f32_16x16x32_bf16 v[126:129], v[134:137], v[166:169], v[126:129]
	v_mfma_f32_16x16x32_bf16 v[122:125], v[142:145], v[166:169], v[122:125]
	v_mfma_f32_16x16x32_bf16 v[110:113], v[134:137], v[174:177], v[110:113]
	v_mfma_f32_16x16x32_bf16 v[106:109], v[142:145], v[174:177], v[106:109]
	v_mfma_f32_16x16x32_bf16 v[94:97], v[134:137], v[182:185], v[94:97]
	v_mfma_f32_16x16x32_bf16 v[90:93], v[142:145], v[182:185], v[90:93]
	v_mfma_f32_16x16x32_bf16 v[78:81], v[134:137], v[190:193], v[78:81]
	v_mfma_f32_16x16x32_bf16 v[74:77], v[142:145], v[190:193], v[74:77]
	v_mfma_f32_16x16x32_bf16 v[126:129], v[138:141], v[170:173], v[126:129]
	v_mfma_f32_16x16x32_bf16 v[122:125], v[146:149], v[170:173], v[122:125]
	v_mfma_f32_16x16x32_bf16 v[110:113], v[138:141], v[178:181], v[110:113]
	v_mfma_f32_16x16x32_bf16 v[106:109], v[146:149], v[178:181], v[106:109]
	v_mfma_f32_16x16x32_bf16 v[94:97], v[138:141], v[186:189], v[94:97]
	v_mfma_f32_16x16x32_bf16 v[90:93], v[146:149], v[186:189], v[90:93]
	v_mfma_f32_16x16x32_bf16 v[78:81], v[138:141], v[206:209], v[78:81]
	v_mfma_f32_16x16x32_bf16 v[74:77], v[146:149], v[206:209], v[74:77]
	v_mfma_f32_16x16x32_bf16 v[118:121], v[150:153], v[166:169], v[118:121]
	v_mfma_f32_16x16x32_bf16 v[114:117], v[158:161], v[166:169], v[114:117]
	v_mfma_f32_16x16x32_bf16 v[102:105], v[150:153], v[174:177], v[102:105]
	v_mfma_f32_16x16x32_bf16 v[98:101], v[158:161], v[174:177], v[98:101]
	v_mfma_f32_16x16x32_bf16 v[86:89], v[150:153], v[182:185], v[86:89]
	v_mfma_f32_16x16x32_bf16 v[82:85], v[158:161], v[182:185], v[82:85]
	v_mfma_f32_16x16x32_bf16 v[70:73], v[150:153], v[190:193], v[70:73]
	v_mfma_f32_16x16x32_bf16 v[66:69], v[158:161], v[190:193], v[66:69]
	v_mfma_f32_16x16x32_bf16 v[118:121], v[154:157], v[170:173], v[118:121]
	v_mfma_f32_16x16x32_bf16 v[114:117], v[162:165], v[170:173], v[114:117]
	v_mfma_f32_16x16x32_bf16 v[102:105], v[154:157], v[178:181], v[102:105]
	v_mfma_f32_16x16x32_bf16 v[98:101], v[162:165], v[178:181], v[98:101]
	v_mfma_f32_16x16x32_bf16 v[86:89], v[154:157], v[186:189], v[86:89]
	v_mfma_f32_16x16x32_bf16 v[82:85], v[162:165], v[186:189], v[82:85]
	v_mfma_f32_16x16x32_bf16 v[70:73], v[154:157], v[206:209], v[70:73]
	v_mfma_f32_16x16x32_bf16 v[66:69], v[162:165], v[206:209], v[66:69]
	s_barrier
	s_add_i32 s24, s25, s19
	v_lshl_add_u64 v[210:211], s[12:13], 0, v[196:197]
	s_mov_b32 m0, s24
	ds_read_b128 v[166:169], v249 offset:16384
	ds_read_b128 v[170:173], v249 offset:17408
	ds_read_b128 v[174:177], v249 offset:18432
	ds_read_b128 v[178:181], v249 offset:19456
	ds_read_b128 v[182:185], v249 offset:20480
	ds_read_b128 v[186:189], v249 offset:21504
	ds_read_b128 v[190:193], v249 offset:22528
	ds_read_b128 v[206:209], v249 offset:23552
	global_load_lds_dwordx4 v[210:211], off
	s_add_i32 m0, s24, 0x2000
	v_lshl_add_u64 v[212:213], s[12:13], 0, v[200:201]
	s_add_u32 s12, s12, s77
	s_addc_u32 s13, s13, 0
	s_add_i32 s8, s8, s19
	global_load_lds_dwordx4 v[212:213], off
	v_lshl_add_u64 v[214:215], s[12:13], 0, v[196:197]
	s_mov_b32 m0, s8
	v_lshl_add_u64 v[216:217], s[12:13], 0, v[200:201]
	global_load_lds_dwordx4 v[214:215], off
	s_add_i32 m0, s8, 0x2000
	v_lshl_add_u64 v[218:219], s[16:17], 0, v[194:195]
	global_load_lds_dwordx4 v[216:217], off
	s_mov_b32 m0, s96
	v_lshl_add_u64 v[220:221], s[16:17], 0, v[198:199]
	global_load_lds_dwordx4 v[218:219], off
	s_mov_b32 m0, s90
	s_nop 0
	global_load_lds_dwordx4 v[220:221], off
	s_waitcnt vmcnt(8)
	s_waitcnt lgkmcnt(0)
	s_barrier
; #define PG8_STAGE(bufoff, gbase, voff) do { _Pragma("unroll") for (int _i = 0; _i < 2; ++_i) \
;         __builtin_amdgcn_global_load_lds((const unsigned*)((const char*)(gbase) + (voff)[_i]), (LAS unsigned*)(lds + (bufoff) + ldsw + _i * 8192), 16, 0, 0); } while (0)
; #define PG8_LDA(dst, b, h) do { _Pragma("unroll") for (int m = 0; m < 4; ++m) _Pragma("unroll") for (int k = 0; k < 2; ++k) dst[m][k] = *(const LAS bf16x8*)(lds + PG8_SA(b, h) + aoff + m * 2048 + k * 1024); } while (0)
; #define PG8_LDB(dst, b, h) do { _Pragma("unroll") for (int n = 0; n < 2; ++n) _Pragma("unroll") for (int k = 0; k < 2; ++k) dst[n][k] = *(const LAS bf16x8*)(lds + PG8_SB(b, h) + boff + n * 2048 + k * 1024); } while (0)
; #define PG8_MMA(ai, bj, At, Bt) do { __builtin_amdgcn_s_setprio(1); _Pragma("unroll") for (int m = 0; m < 4; ++m) _Pragma("unroll") for (int n = 0; n < 2; ++n) _Pragma("unroll") for (int k = 0; k < 2; ++k) \
;         acc[ai][bj][m][n] = __builtin_amdgcn_mfma_f32_16x16x32_bf16(Bt[n][k], At[m][k], acc[ai][bj][m][n], 0, 0, 0); __builtin_amdgcn_s_setprio(0); } while (0)
; #define PG8_WAIT_V(n) asm volatile("s_waitcnt vmcnt(" #n ")" ::: "memory")
; #define PG8_WAIT_L(n) asm volatile("s_waitcnt lgkmcnt(" #n ")" ::: "memory")
; #define PG8_BAR __builtin_amdgcn_s_barrier()
; #define PG8_SCHED __builtin_amdgcn_sched_barrier(0)
; DI void gemm_phase(LAS unsigned char* lds, const Sched& S, const Epi& Ep) {
;     ...
;             PG8_WAIT_V(8); PG8_WAIT_L(0); PG8_BAR; PG8_MMA(1, 0, At, B0); PG8_MMA(1, 1, At, B1); PG8_BAR; PG8_SCHED;
;             PG8_LDB(B0, 1, 0); PG8_LDB(B1, 1, 1); PG8_SCHED; PG8_LDA(At, 1, 0); PG8_STAGE(PG8_SA(0, 1), a2 + hstepA, voffA);
;             PG8_WAIT_V(8); PG8_WAIT_L(0); PG8_BAR; PG8_MMA(0, 0, At, B0); PG8_MMA(0, 1, At, B1); PG8_BAR; PG8_SCHED;
	s_waitcnt lgkmcnt(0)
	v_mfma_f32_16x16x32_bf16 v[62:65], v[134:137], v[166:169], v[62:65]
	v_mfma_f32_16x16x32_bf16 v[58:61], v[142:145], v[166:169], v[58:61]
	v_mfma_f32_16x16x32_bf16 v[46:49], v[134:137], v[174:177], v[46:49]
	v_mfma_f32_16x16x32_bf16 v[42:45], v[142:145], v[174:177], v[42:45]
	v_mfma_f32_16x16x32_bf16 v[30:33], v[134:137], v[182:185], v[30:33]
	v_mfma_f32_16x16x32_bf16 v[26:29], v[142:145], v[182:185], v[26:29]
	v_mfma_f32_16x16x32_bf16 v[14:17], v[134:137], v[190:193], v[14:17]
	v_mfma_f32_16x16x32_bf16 v[10:13], v[142:145], v[190:193], v[10:13]
	v_mfma_f32_16x16x32_bf16 v[62:65], v[138:141], v[170:173], v[62:65]
	v_mfma_f32_16x16x32_bf16 v[58:61], v[146:149], v[170:173], v[58:61]
	v_mfma_f32_16x16x32_bf16 v[46:49], v[138:141], v[178:181], v[46:49]
	v_mfma_f32_16x16x32_bf16 v[42:45], v[146:149], v[178:181], v[42:45]
	v_mfma_f32_16x16x32_bf16 v[30:33], v[138:141], v[186:189], v[30:33]
	v_mfma_f32_16x16x32_bf16 v[26:29], v[146:149], v[186:189], v[26:29]
	v_mfma_f32_16x16x32_bf16 v[14:17], v[138:141], v[206:209], v[14:17]
	v_mfma_f32_16x16x32_bf16 v[10:13], v[146:149], v[206:209], v[10:13]
	v_mfma_f32_16x16x32_bf16 v[54:57], v[150:153], v[166:169], v[54:57]
	v_mfma_f32_16x16x32_bf16 v[50:53], v[158:161], v[166:169], v[50:53]
	v_mfma_f32_16x16x32_bf16 v[38:41], v[150:153], v[174:177], v[38:41]
	v_mfma_f32_16x16x32_bf16 v[34:37], v[158:161], v[174:177], v[34:37]
	v_mfma_f32_16x16x32_bf16 v[22:25], v[150:153], v[182:185], v[22:25]
	v_mfma_f32_16x16x32_bf16 v[18:21], v[158:161], v[182:185], v[18:21]
	v_mfma_f32_16x16x32_bf16 v[6:9], v[150:153], v[190:193], v[6:9]
	v_mfma_f32_16x16x32_bf16 v[2:5], v[158:161], v[190:193], v[2:5]
	v_mfma_f32_16x16x32_bf16 v[54:57], v[154:157], v[170:173], v[54:57]
	v_mfma_f32_16x16x32_bf16 v[50:53], v[162:165], v[170:173], v[50:53]
	v_mfma_f32_16x16x32_bf16 v[38:41], v[154:157], v[178:181], v[38:41]
	v_mfma_f32_16x16x32_bf16 v[34:37], v[162:165], v[178:181], v[34:37]
	v_mfma_f32_16x16x32_bf16 v[22:25], v[154:157], v[186:189], v[22:25]
	v_mfma_f32_16x16x32_bf16 v[18:21], v[162:165], v[186:189], v[18:21]
	v_mfma_f32_16x16x32_bf16 v[6:9], v[154:157], v[206:209], v[6:9]
	v_mfma_f32_16x16x32_bf16 v[2:5], v[162:165], v[206:209], v[2:5]
	s_barrier
	s_add_i32 s8, 0, 0x18000
	v_add_u32_e32 v0, s8, v252
	s_add_i32 s24, 0, 0x1c000
	ds_read_b128 v[134:137], v0
	ds_read_b128 v[138:141], v0 offset:1024
	ds_read_b128 v[142:145], v0 offset:2048
	ds_read_b128 v[146:149], v0 offset:3072
	v_add_u32_e32 v0, s24, v252
	ds_read_b128 v[150:153], v0
	ds_read_b128 v[154:157], v0 offset:1024
	ds_read_b128 v[158:161], v0 offset:2048
	ds_read_b128 v[162:165], v0 offset:3072
	s_add_u32 s12, s16, s6
	s_addc_u32 s13, s17, 0
	s_mov_b32 m0, s91
	v_lshl_add_u64 v[222:223], s[12:13], 0, v[194:195]
	ds_read_b128 v[166:169], v249 offset:32768
	ds_read_b128 v[170:173], v249 offset:33792
	ds_read_b128 v[174:177], v249 offset:34816
	ds_read_b128 v[178:181], v249 offset:35840
	ds_read_b128 v[182:185], v249 offset:36864
	ds_read_b128 v[186:189], v249 offset:37888
	ds_read_b128 v[190:193], v249 offset:38912
	ds_read_b128 v[206:209], v249 offset:39936
	global_load_lds_dwordx4 v[222:223], off
	v_lshl_add_u64 v[222:223], s[12:13], 0, v[198:199]
	s_mov_b32 m0, s28
	s_nop 0
	global_load_lds_dwordx4 v[222:223], off
	s_waitcnt vmcnt(8)
	s_waitcnt lgkmcnt(0)
	s_barrier
	s_waitcnt lgkmcnt(0)
	v_mfma_f32_16x16x32_bf16 v[126:129], v[134:137], v[166:169], v[126:129]
	v_mfma_f32_16x16x32_bf16 v[122:125], v[142:145], v[166:169], v[122:125]
	v_mfma_f32_16x16x32_bf16 v[110:113], v[134:137], v[174:177], v[110:113]
	v_mfma_f32_16x16x32_bf16 v[106:109], v[142:145], v[174:177], v[106:109]
	v_mfma_f32_16x16x32_bf16 v[94:97], v[134:137], v[182:185], v[94:97]
	v_mfma_f32_16x16x32_bf16 v[90:93], v[142:145], v[182:185], v[90:93]
	v_mfma_f32_16x16x32_bf16 v[78:81], v[134:137], v[190:193], v[78:81]
	v_mfma_f32_16x16x32_bf16 v[74:77], v[142:145], v[190:193], v[74:77]
	v_mfma_f32_16x16x32_bf16 v[126:129], v[138:141], v[170:173], v[126:129]
	v_mfma_f32_16x16x32_bf16 v[122:125], v[146:149], v[170:173], v[122:125]
	v_mfma_f32_16x16x32_bf16 v[110:113], v[138:141], v[178:181], v[110:113]
	v_mfma_f32_16x16x32_bf16 v[106:109], v[146:149], v[178:181], v[106:109]
	v_mfma_f32_16x16x32_bf16 v[94:97], v[138:141], v[186:189], v[94:97]
	v_mfma_f32_16x16x32_bf16 v[90:93], v[146:149], v[186:189], v[90:93]
	v_mfma_f32_16x16x32_bf16 v[78:81], v[138:141], v[206:209], v[78:81]
	v_mfma_f32_16x16x32_bf16 v[74:77], v[146:149], v[206:209], v[74:77]
	v_mfma_f32_16x16x32_bf16 v[118:121], v[150:153], v[166:169], v[118:121]
	v_mfma_f32_16x16x32_bf16 v[114:117], v[158:161], v[166:169], v[114:117]
	v_mfma_f32_16x16x32_bf16 v[102:105], v[150:153], v[174:177], v[102:105]
	v_mfma_f32_16x16x32_bf16 v[98:101], v[158:161], v[174:177], v[98:101]
	v_mfma_f32_16x16x32_bf16 v[86:89], v[150:153], v[182:185], v[86:89]
	v_mfma_f32_16x16x32_bf16 v[82:85], v[158:161], v[182:185], v[82:85]
	v_mfma_f32_16x16x32_bf16 v[70:73], v[150:153], v[190:193], v[70:73]
	v_mfma_f32_16x16x32_bf16 v[66:69], v[158:161], v[190:193], v[66:69]
	v_mfma_f32_16x16x32_bf16 v[118:121], v[154:157], v[170:173], v[118:121]
	v_mfma_f32_16x16x32_bf16 v[114:117], v[162:165], v[170:173], v[114:117]
	v_mfma_f32_16x16x32_bf16 v[102:105], v[154:157], v[178:181], v[102:105]
	v_mfma_f32_16x16x32_bf16 v[98:101], v[162:165], v[178:181], v[98:101]
	v_mfma_f32_16x16x32_bf16 v[86:89], v[154:157], v[186:189], v[86:89]
	v_mfma_f32_16x16x32_bf16 v[82:85], v[162:165], v[186:189], v[82:85]
	v_mfma_f32_16x16x32_bf16 v[70:73], v[154:157], v[206:209], v[70:73]
	v_mfma_f32_16x16x32_bf16 v[66:69], v[162:165], v[206:209], v[66:69]
	s_barrier
; #define PG8_STAGE(bufoff, gbase, voff) do { _Pragma("unroll") for (int _i = 0; _i < 2; ++_i) \
;         __builtin_amdgcn_global_load_lds((const unsigned*)((const char*)(gbase) + (voff)[_i]), (LAS unsigned*)(lds + (bufoff) + ldsw + _i * 8192), 16, 0, 0); } while (0)
; #define PG8_LDA(dst, b, h) do { _Pragma("unroll") for (int m = 0; m < 4; ++m) _Pragma("unroll") for (int k = 0; k < 2; ++k) dst[m][k] = *(const LAS bf16x8*)(lds + PG8_SA(b, h) + aoff + m * 2048 + k * 1024); } while (0)
; #define PG8_MMA(ai, bj, At, Bt) do { __builtin_amdgcn_s_setprio(1); _Pragma("unroll") for (int m = 0; m < 4; ++m) _Pragma("unroll") for (int n = 0; n < 2; ++n) _Pragma("unroll") for (int k = 0; k < 2; ++k) \
;         acc[ai][bj][m][n] = __builtin_amdgcn_mfma_f32_16x16x32_bf16(Bt[n][k], At[m][k], acc[ai][bj][m][n], 0, 0, 0); __builtin_amdgcn_s_setprio(0); } while (0)
; #define PG8_WAIT_V(n) asm volatile("s_waitcnt vmcnt(" #n ")" ::: "memory")
; #define PG8_WAIT_L(n) asm volatile("s_waitcnt lgkmcnt(" #n ")" ::: "memory")
; #define PG8_BAR __builtin_amdgcn_s_barrier()
; #define PG8_SCHED __builtin_amdgcn_sched_barrier(0)
; DI void gemm_phase(LAS unsigned char* lds, const Sched& S, const Epi& Ep) {
;     ...
;             PG8_LDA(At, 1, 1); PG8_STAGE(PG8_SB(1, 0), b3, voffB); PG8_STAGE(PG8_SB(1, 1), b3 + hstepB, voffB); PG8_STAGE(PG8_SA(1, 0), a3, voffA);
;             PG8_WAIT_V(8); PG8_WAIT_L(0); PG8_BAR; PG8_MMA(1, 0, At, B0); PG8_MMA(1, 1, At, B1); PG8_BAR; PG8_SCHED;
;         }
;         if (align_epi) { if (wr == 0) PG8_BAR; }
	s_add_i32 s8, s8, s19
	v_lshl_add_u64 v[210:211], v[210:211], 0, s[26:27]
	s_mov_b32 m0, s8
	ds_read_b128 v[166:169], v249 offset:49152
	ds_read_b128 v[170:173], v249 offset:50176
	ds_read_b128 v[174:177], v249 offset:51200
	ds_read_b128 v[178:181], v249 offset:52224
	ds_read_b128 v[182:185], v249 offset:53248
	ds_read_b128 v[186:189], v249 offset:54272
	ds_read_b128 v[190:193], v249 offset:55296
	ds_read_b128 v[206:209], v249 offset:56320
	global_load_lds_dwordx4 v[210:211], off
	v_lshl_add_u64 v[210:211], v[212:213], 0, s[26:27]
	s_add_i32 m0, s8, 0x2000
	s_add_i32 s8, s24, s19
	global_load_lds_dwordx4 v[210:211], off
	v_lshl_add_u64 v[210:211], v[214:215], 0, s[26:27]
	s_mov_b32 m0, s8
	s_nop 0
	global_load_lds_dwordx4 v[210:211], off
	v_lshl_add_u64 v[210:211], v[216:217], 0, s[26:27]
	s_add_i32 m0, s8, 0x2000
	s_nop 0
	global_load_lds_dwordx4 v[210:211], off
	v_lshl_add_u64 v[210:211], v[218:219], 0, s[26:27]
	s_mov_b32 m0, s89
	s_nop 0
	global_load_lds_dwordx4 v[210:211], off
	v_lshl_add_u64 v[210:211], v[220:221], 0, s[26:27]
	s_mov_b32 m0, s34
	s_nop 0
	global_load_lds_dwordx4 v[210:211], off
	s_waitcnt vmcnt(8)
	s_waitcnt lgkmcnt(0)
	s_barrier
	s_waitcnt lgkmcnt(0)
	v_mfma_f32_16x16x32_bf16 v[62:65], v[134:137], v[166:169], v[62:65]
	v_mfma_f32_16x16x32_bf16 v[58:61], v[142:145], v[166:169], v[58:61]
	v_mfma_f32_16x16x32_bf16 v[46:49], v[134:137], v[174:177], v[46:49]
	v_mfma_f32_16x16x32_bf16 v[42:45], v[142:145], v[174:177], v[42:45]
	v_mfma_f32_16x16x32_bf16 v[30:33], v[134:137], v[182:185], v[30:33]
	v_mfma_f32_16x16x32_bf16 v[26:29], v[142:145], v[182:185], v[26:29]
	v_mfma_f32_16x16x32_bf16 v[14:17], v[134:137], v[190:193], v[14:17]
	v_mfma_f32_16x16x32_bf16 v[10:13], v[142:145], v[190:193], v[10:13]
	v_mfma_f32_16x16x32_bf16 v[62:65], v[138:141], v[170:173], v[62:65]
	v_mfma_f32_16x16x32_bf16 v[58:61], v[146:149], v[170:173], v[58:61]
	v_mfma_f32_16x16x32_bf16 v[46:49], v[138:141], v[178:181], v[46:49]
	v_mfma_f32_16x16x32_bf16 v[42:45], v[146:149], v[178:181], v[42:45]
	v_mfma_f32_16x16x32_bf16 v[30:33], v[138:141], v[186:189], v[30:33]
	v_mfma_f32_16x16x32_bf16 v[26:29], v[146:149], v[186:189], v[26:29]
	v_mfma_f32_16x16x32_bf16 v[14:17], v[138:141], v[206:209], v[14:17]
	v_mfma_f32_16x16x32_bf16 v[10:13], v[146:149], v[206:209], v[10:13]
	v_mfma_f32_16x16x32_bf16 v[54:57], v[150:153], v[166:169], v[54:57]
	v_mfma_f32_16x16x32_bf16 v[50:53], v[158:161], v[166:169], v[50:53]
	v_mfma_f32_16x16x32_bf16 v[38:41], v[150:153], v[174:177], v[38:41]
	v_mfma_f32_16x16x32_bf16 v[34:37], v[158:161], v[174:177], v[34:37]
	v_mfma_f32_16x16x32_bf16 v[22:25], v[150:153], v[182:185], v[22:25]
	v_mfma_f32_16x16x32_bf16 v[18:21], v[158:161], v[182:185], v[18:21]
	v_mfma_f32_16x16x32_bf16 v[6:9], v[150:153], v[190:193], v[6:9]
	v_mfma_f32_16x16x32_bf16 v[2:5], v[158:161], v[190:193], v[2:5]
	v_mfma_f32_16x16x32_bf16 v[54:57], v[154:157], v[170:173], v[54:57]
	v_mfma_f32_16x16x32_bf16 v[50:53], v[162:165], v[170:173], v[50:53]
	v_mfma_f32_16x16x32_bf16 v[38:41], v[154:157], v[178:181], v[38:41]
	v_mfma_f32_16x16x32_bf16 v[34:37], v[162:165], v[178:181], v[34:37]
	v_mfma_f32_16x16x32_bf16 v[22:25], v[154:157], v[186:189], v[22:25]
	v_mfma_f32_16x16x32_bf16 v[18:21], v[162:165], v[186:189], v[18:21]
	v_mfma_f32_16x16x32_bf16 v[6:9], v[154:157], v[206:209], v[6:9]
	v_mfma_f32_16x16x32_bf16 v[2:5], v[162:165], v[206:209], v[2:5]
	s_barrier
	s_add_u32 s44, s44, 0x100
	s_addc_u32 s45, s45, 0
	s_cmp_ge_u32 s3, s97
	s_cbranch_scc0 .LBB0_370
	s_and_b64 vcc, exec, s[82:83]
	s_cbranch_vccz .LBB0_373
	s_barrier

; DI void xcd_barrier(const XcdBarrier& b) {
;     asm volatile("s_waitcnt vmcnt(0)" ::: "memory");
;     __syncthreads();
;     if (threadIdx.x == 0) {
;         unsigned* bar = b.bar;
;         __builtin_amdgcn_s_waitcnt(0);
;         unsigned nloc = b.st[0], nx = b.st[1];
;         if (nloc == 0u) { xcd_barrier_complete(bar, b.x, nloc, nx); b.st[0] = nloc; b.st[1] = nx; }
; __global__ void __launch_bounds__(NTH, 2) fwd_megakernel(Params P0) {
;     ...
;             pg8::gemm_phase(lds, S, E);
;         }
;         }
;         if (ph + 1 < nph) xcd_barrier(xbar);
.LBB0_495:
	s_setprio 0
	s_add_i32 s0, s87, 1
	v_readlane_b32 s76, v254, 56
	v_readlane_b32 s74, v254, 44
	s_mov_b32 s78, s64
	s_cmp_ge_i32 s0, s79
	v_readlane_b32 s77, v254, 57
	v_readlane_b32 s85, v254, 58
	v_readlane_b32 s96, v254, 59
	v_readlane_b32 s75, v254, 45
	s_movk_i32 s84, 0x80
	s_mov_b32 s97, 0x43160a51
	v_readlane_b32 s22, v254, 42
	v_readlane_b32 s23, v254, 43
	s_cbranch_scc1 .LBB0_21
	s_waitcnt vmcnt(0)
	s_waitcnt vmcnt(0) lgkmcnt(0)
	s_barrier
	s_mov_b64 s[0:1], exec
	v_readlane_b32 s2, v253, 0
	v_readlane_b32 s3, v253, 1
	v_readlane_b32 s24, v253, 2
	v_readlane_b32 s12, v253, 4
	v_readlane_b32 s16, v253, 6
	v_readlane_b32 s18, v253, 8
	v_readlane_b32 s20, v253, 10
	v_readlane_b32 s30, v253, 46
	s_and_b64 s[2:3], s[0:1], s[2:3]
	v_readlane_b32 s25, v253, 3
	v_readlane_b32 s13, v253, 5
	v_readlane_b32 s17, v253, 7
	v_readlane_b32 s19, v253, 9
	v_readlane_b32 s21, v253, 11
	v_readlane_b32 s31, v253, 47
	s_mov_b64 exec, s[2:3]
	s_cbranch_execz .LBB0_20
	v_readlane_b32 s2, v254, 24
	s_waitcnt vmcnt(0) expcnt(0) lgkmcnt(0)
	s_nop 0
	v_mov_b32_e32 v0, s2
	ds_read_b32 v3, v0
	v_readlane_b32 s2, v254, 25
	s_waitcnt lgkmcnt(0)
	v_cmp_ne_u32_e32 vcc, 0, v3
	v_mov_b32_e32 v0, s2
	ds_read_b32 v2, v0
	s_cbranch_vccnz .LBB0_514
	s_mov_b32 s8, 1
	s_branch .LBB0_500
